# waitcnt placement: redundant vmcnt(0) removed from the P9 peeled tile
# speedup vs baseline: 1.0044x; 1.0044x over previous
.LBB0_1359:
	s_cmp_gt_i32 s52, s51
	s_cselect_b64 s[2:3], -1, 0
	s_or_b64 s[2:3], s[44:45], s[2:3]
	s_and_b64 vcc, exec, s[2:3]
	s_cbranch_vccnz .LBB0_1368
	s_xor_b64 s[4:5], s[4:5], -1
	s_bitcmp1_b32 s52, 0
	s_cselect_b32 s2, 0x5c00, 0
	s_add_i32 s2, s2, 0
	v_add3_u32 v120, s2, v173, v144
	ds_read_b128 v[64:67], v120
	ds_read_b128 v[68:71], v120 offset:32
	ds_read_b128 v[72:75], v120 offset:64
	ds_read_b128 v[76:79], v120 offset:96
	ds_read_b128 v[104:107], v120 offset:4608
	ds_read_b128 v[108:111], v120 offset:4640
	ds_read_b128 v[112:115], v120 offset:4672
	ds_read_b128 v[116:119], v120 offset:4704
	s_waitcnt lgkmcnt(7)
	v_mfma_f32_32x32x16_bf16 v[48:63], v[64:67], v[100:103], v[0:15]
	s_waitcnt lgkmcnt(3)
	v_mfma_f32_32x32x16_bf16 v[0:15], v[104:107], v[100:103], v[0:15]
	v_mfma_f32_32x32x16_bf16 v[48:63], v[68:71], v[96:99], v[48:63]
	s_waitcnt lgkmcnt(2)
	v_mfma_f32_32x32x16_bf16 v[0:15], v[108:111], v[96:99], v[0:15]
	v_mfma_f32_32x32x16_bf16 v[48:63], v[72:75], v[92:95], v[48:63]
	v_add3_u32 v72, s2, v171, v144
	ds_read_b128 v[64:67], v72 offset:18432
	ds_read_b128 v[68:71], v72 offset:18464
	s_waitcnt lgkmcnt(3)
	v_mfma_f32_32x32x16_bf16 v[0:15], v[112:115], v[92:95], v[0:15]
	v_mfma_f32_32x32x16_bf16 v[48:63], v[76:79], v[88:91], v[48:63]
	s_waitcnt lgkmcnt(2)
	v_mfma_f32_32x32x16_bf16 v[0:15], v[116:119], v[88:91], v[0:15]
	s_waitcnt lgkmcnt(1)
	v_mfma_f32_32x32x16_bf16 v[48:63], v[64:67], v[84:87], v[48:63]
	ds_read_b128 v[64:67], v72 offset:20992
	ds_read_b128 v[72:75], v72 offset:21024
	s_waitcnt lgkmcnt(1)
	v_mfma_f32_32x32x16_bf16 v[0:15], v[64:67], v[84:87], v[0:15]
	ds_read_b128 v[112:115], v120 offset:9216
	ds_read_b128 v[104:107], v120 offset:9248
	ds_read_b128 v[96:99], v120 offset:9280
	ds_read_b128 v[88:91], v120 offset:9312
	ds_read_b128 v[108:111], v120 offset:13824
	ds_read_b128 v[100:103], v120 offset:13856
	ds_read_b128 v[92:95], v120 offset:13888
	ds_read_b128 v[84:87], v120 offset:13920
	v_mfma_f32_32x32x16_bf16 v[48:63], v[68:71], v[80:83], v[48:63]
	s_waitcnt lgkmcnt(8)
	v_mfma_f32_32x32x16_bf16 v[0:15], v[72:75], v[80:83], v[0:15]
	s_nop 9
	v_max_f32_e32 v64, v49, v49
	v_max_f32_e32 v65, v48, v48
	v_max_f32_e32 v64, v65, v64
	v_max3_f32 v64, v64, v50, v51
	v_max3_f32 v64, v64, v52, v53
	v_max3_f32 v64, v64, v54, v55
	v_max3_f32 v64, v64, v56, v57
	v_max3_f32 v64, v64, v58, v59
	v_max3_f32 v64, v64, v60, v61
	v_max3_f32 v64, v64, v62, v63
	v_max3_f32 v64, v64, v0, v1
	v_max3_f32 v64, v64, v2, v3
	v_max3_f32 v64, v64, v4, v5
	v_max3_f32 v64, v64, v6, v7
	v_max3_f32 v64, v64, v8, v9
	v_max3_f32 v64, v64, v10, v11
	v_max3_f32 v64, v64, v12, v13
	v_max3_f32 v64, v64, v14, v15
	v_mov_b32_e32 v65, v64
	s_nop 1
	v_permlane32_swap_b32_e32 v65, v64
	s_andn2_b64 vcc, exec, s[4:5]
	v_max_f32_e32 v80, v64, v65
	v_cndmask_b32_e64 v64, 0, 1, s[4:5]
	v_cmp_ne_u32_e64 s[2:3], 1, v64
	s_mov_b64 s[4:5], -1
	s_cbranch_vccnz .LBB0_1363
	v_cmp_lt_f32_e32 vcc, s72, v80
	s_cbranch_vccz .LBB0_1370
	v_max_f32_e32 v64, v80, v80
	v_max_f32_e32 v80, 0, v64
